# stack19 with the C-layer attention epilogue's LDS tile done in a single pass (32 rows per wave; waves 0-3 use the idle tail of the V image, waves 4-7 the area above the bias table)
# baseline (speedup 1.0000x reference)
.LBB0_250:
	v_and_b32_e32 v3, 64, v158
	v_xor_b32_e32 v2, 32, v158
	v_add_u32_e32 v3, 64, v3
	s_lshl_b64 s[98:99], s[60:61], 25
	v_cmp_lt_i32_e32 vcc, v2, v3
	s_add_u32 s67, s70, s98
	s_addc_u32 s73, s71, s99
	v_cndmask_b32_e32 v2, v158, v2, vcc
	v_lshlrev_b32_e32 v91, 2, v2
	s_add_u32 s67, s67, 0xfe000000
	ds_bpermute_b32 v2, v91, v138
	s_addc_u32 s73, s73, -1
	s_cmp_eq_u32 s60, 0
	s_cselect_b32 s67, s30, s67
	s_cselect_b32 s73, s31, s73
	s_add_u32 s64, s67, s64
	s_addc_u32 s65, s73, s65
	v_mov_b32_e32 v93, v1
	s_waitcnt lgkmcnt(0)
	v_add_f32_e32 v2, v138, v2
	v_lshl_add_u64 v[96:97], s[64:65], 0, v[92:93]
	v_div_scale_f32 v3, s[64:65], v2, v2, 1.0
	v_rcp_f32_e32 v4, v3
	s_lshl_b64 s[60:61], s[60:61], 20
	s_add_u32 s60, s96, s60
	s_addc_u32 s61, s97, s61
	v_fma_f32 v5, -v3, v4, 1.0
	v_fmac_f32_e32 v4, v5, v4
	v_div_scale_f32 v5, vcc, 1.0, v2, 1.0
	v_mul_f32_e32 v6, v5, v4
	v_fma_f32 v7, -v3, v6, v5
	v_fmac_f32_e32 v6, v7, v4
	v_fma_f32 v3, -v3, v6, v5
	v_div_fmas_f32 v3, v3, v4, v6
	v_div_fixup_f32 v3, v3, v2, 1.0
	v_readlane_b32 s100, v248, 28
	s_nop 0
	s_cmp_eq_u32 s100, 3
	s_cbranch_scc1 .LattnA_0
	s_add_u32 s0, s60, s0
	s_addc_u32 s1, s61, s1
	v_mul_f32_e32 v218, v16, v3
	v_mul_f32_e32 v219, v17, v3
	v_cvt_pk_bf16_f32 v200, v218, v219
	v_mul_f32_e32 v218, v18, v3
	v_mul_f32_e32 v219, v19, v3
	v_cvt_pk_bf16_f32 v201, v218, v219
	v_mul_f32_e32 v218, v32, v3
	v_mul_f32_e32 v219, v33, v3
	v_cvt_pk_bf16_f32 v208, v218, v219
	v_mul_f32_e32 v218, v34, v3
	v_mul_f32_e32 v219, v35, v3
	v_cvt_pk_bf16_f32 v209, v218, v219
	v_mul_f32_e32 v218, v20, v3
	v_mul_f32_e32 v219, v21, v3
	v_cvt_pk_bf16_f32 v202, v218, v219
	v_mul_f32_e32 v218, v22, v3
	v_mul_f32_e32 v219, v23, v3
	v_cvt_pk_bf16_f32 v203, v218, v219
	v_mul_f32_e32 v218, v36, v3
	v_mul_f32_e32 v219, v37, v3
	v_cvt_pk_bf16_f32 v210, v218, v219
	v_mul_f32_e32 v218, v38, v3
	v_mul_f32_e32 v219, v39, v3
	v_cvt_pk_bf16_f32 v211, v218, v219
	v_mul_f32_e32 v218, v24, v3
	v_mul_f32_e32 v219, v25, v3
	v_cvt_pk_bf16_f32 v204, v218, v219
	v_mul_f32_e32 v218, v26, v3
	v_mul_f32_e32 v219, v27, v3
	v_cvt_pk_bf16_f32 v205, v218, v219
	v_mul_f32_e32 v218, v40, v3
	v_mul_f32_e32 v219, v41, v3
	v_cvt_pk_bf16_f32 v212, v218, v219
	v_mul_f32_e32 v218, v42, v3
	v_mul_f32_e32 v219, v43, v3
	v_cvt_pk_bf16_f32 v213, v218, v219
	v_mul_f32_e32 v218, v28, v3
	v_mul_f32_e32 v219, v29, v3
	v_cvt_pk_bf16_f32 v206, v218, v219
	v_mul_f32_e32 v218, v30, v3
	v_mul_f32_e32 v219, v31, v3
	v_cvt_pk_bf16_f32 v207, v218, v219
	v_mul_f32_e32 v218, v44, v3
	v_mul_f32_e32 v219, v45, v3
	v_cvt_pk_bf16_f32 v214, v218, v219
	v_mul_f32_e32 v218, v46, v3
	v_mul_f32_e32 v219, v47, v3
	v_cvt_pk_bf16_f32 v215, v218, v219
	v_lshrrev_b32_e32 v216, 5, v158
	v_and_b32_e32 v217, 31, v158
	v_lshrrev_b32_e32 v218, 6, v150
	v_lshrrev_b32_e32 v219, 2, v218
	v_mul_u32_u24_e32 v218, 0x1200, v218
	v_mul_u32_u24_e32 v219, 0x4450, v219
	v_add3_u32 v218, v218, v219, 0
	v_mov_b32_e32 v221, 0x19800
	v_mul_u32_u24_e32 v219, 0x90, v217
	v_lshl_add_u32 v220, v216, 4, v219
	v_add3_u32 v220, v220, v218, v221
	v_lshrrev_b32_e32 v223, 3, v158
	v_and_b32_e32 v224, 7, v158
	v_mul_u32_u24_e32 v222, 0x90, v223
	v_lshl_add_u32 v222, v224, 4, v222
	v_add3_u32 v222, v222, v218, v221
	v_lshlrev_b32_e32 v228, 4, v224
	v_lshlrev_b32_e32 v229, 3, v216
	v_sub_u32_e32 v228, v228, v229
	v_ashrrev_i32_e32 v229, 31, v228
	v_lshl_add_u64 v[226:227], v[96:97], 0, v[228:229]
	v_readlane_b32 s100, v94, 0
	v_readlane_b32 s101, v95, 0
	v_permlane32_swap_b32_e32 v200, v202
	v_permlane32_swap_b32_e32 v201, v203
	v_permlane32_swap_b32_e32 v204, v206
	v_permlane32_swap_b32_e32 v205, v207
	v_permlane32_swap_b32_e32 v208, v210
	v_permlane32_swap_b32_e32 v209, v211
	v_permlane32_swap_b32_e32 v212, v214
	v_permlane32_swap_b32_e32 v213, v215
	s_nop 0
	ds_write_b128 v220, v[200:203]
	ds_write_b128 v220, v[204:207] offset:32
	ds_write_b128 v220, v[208:211] offset:64
	ds_write_b128 v220, v[212:215] offset:96
	v_add_u32_e32 v238, 0, v223
	v_mov_b32_e32 v240, s100
	v_mov_b32_e32 v241, s101
	v_mad_u64_u32 v[240:241], vcc, v238, s93, v[240:241]
	v_lshlrev_b64 v[240:241], 11, v[240:241]
	v_lshl_add_u64 v[240:241], v[240:241], 0, v[226:227]
	v_add_u32_e32 v238, 8, v223
	v_mov_b32_e32 v242, s100
	v_mov_b32_e32 v243, s101
	v_mad_u64_u32 v[242:243], vcc, v238, s93, v[242:243]
	v_lshlrev_b64 v[242:243], 11, v[242:243]
	v_lshl_add_u64 v[242:243], v[242:243], 0, v[226:227]
	v_add_u32_e32 v238, 16, v223
	v_mov_b32_e32 v244, s100
	v_mov_b32_e32 v245, s101
	v_mad_u64_u32 v[244:245], vcc, v238, s93, v[244:245]
	v_lshlrev_b64 v[244:245], 11, v[244:245]
	v_lshl_add_u64 v[244:245], v[244:245], 0, v[226:227]
	v_add_u32_e32 v238, 24, v223
	v_mov_b32_e32 v246, s100
	v_mov_b32_e32 v247, s101
	v_mad_u64_u32 v[246:247], vcc, v238, s93, v[246:247]
	v_lshlrev_b64 v[246:247], 11, v[246:247]
	v_lshl_add_u64 v[246:247], v[246:247], 0, v[226:227]
	s_waitcnt lgkmcnt(0)
	ds_read_b128 v[200:203], v222
	ds_read_b128 v[204:207], v222 offset:1152
	ds_read_b128 v[208:211], v222 offset:2304
	ds_read_b128 v[212:215], v222 offset:3456
	s_waitcnt lgkmcnt(3)
	global_store_dwordx4 v[240:241], v[200:203], off
	s_waitcnt lgkmcnt(2)
	global_store_dwordx4 v[242:243], v[204:207], off
	s_waitcnt lgkmcnt(1)
	global_store_dwordx4 v[244:245], v[208:211], off
	s_waitcnt lgkmcnt(0)
	global_store_dwordx4 v[246:247], v[212:215], off
	s_branch .LattnJ_0

.LBB0_263:
	ds_bpermute_b32 v2, v91, v93
	s_waitcnt lgkmcnt(0)
	v_add_f32_e32 v2, v93, v2
	v_div_scale_f32 v3, s[16:17], v2, v2, 1.0
	v_rcp_f32_e32 v4, v3
	s_nop 0
	v_fma_f32 v5, -v3, v4, 1.0
	v_fmac_f32_e32 v4, v5, v4
	v_div_scale_f32 v5, vcc, 1.0, v2, 1.0
	v_mul_f32_e32 v6, v5, v4
	v_fma_f32 v7, -v3, v6, v5
	v_fmac_f32_e32 v6, v7, v4
	v_fma_f32 v3, -v3, v6, v5
	v_div_fmas_f32 v3, v3, v4, v6
	v_div_fixup_f32 v3, v3, v2, 1.0
	v_readlane_b32 s100, v248, 28
	s_nop 0
	s_cmp_eq_u32 s100, 3
	s_cbranch_scc1 .LattnA_1
	v_mul_f32_e32 v218, v16, v3
	v_mul_f32_e32 v219, v17, v3
	v_cvt_pk_bf16_f32 v200, v218, v219
	v_mul_f32_e32 v218, v18, v3
	v_mul_f32_e32 v219, v19, v3
	v_cvt_pk_bf16_f32 v201, v218, v219
	v_mul_f32_e32 v218, v32, v3
	v_mul_f32_e32 v219, v33, v3
	v_cvt_pk_bf16_f32 v208, v218, v219
	v_mul_f32_e32 v218, v34, v3
	v_mul_f32_e32 v219, v35, v3
	v_cvt_pk_bf16_f32 v209, v218, v219
	v_mul_f32_e32 v218, v20, v3
	v_mul_f32_e32 v219, v21, v3
	v_cvt_pk_bf16_f32 v202, v218, v219
	v_mul_f32_e32 v218, v22, v3
	v_mul_f32_e32 v219, v23, v3
	v_cvt_pk_bf16_f32 v203, v218, v219
	v_mul_f32_e32 v218, v36, v3
	v_mul_f32_e32 v219, v37, v3
	v_cvt_pk_bf16_f32 v210, v218, v219
	v_mul_f32_e32 v218, v38, v3
	v_mul_f32_e32 v219, v39, v3
	v_cvt_pk_bf16_f32 v211, v218, v219
	v_mul_f32_e32 v218, v24, v3
	v_mul_f32_e32 v219, v25, v3
	v_cvt_pk_bf16_f32 v204, v218, v219
	v_mul_f32_e32 v218, v26, v3
	v_mul_f32_e32 v219, v27, v3
	v_cvt_pk_bf16_f32 v205, v218, v219
	v_mul_f32_e32 v218, v40, v3
	v_mul_f32_e32 v219, v41, v3
	v_cvt_pk_bf16_f32 v212, v218, v219
	v_mul_f32_e32 v218, v42, v3
	v_mul_f32_e32 v219, v43, v3
	v_cvt_pk_bf16_f32 v213, v218, v219
	v_mul_f32_e32 v218, v28, v3
	v_mul_f32_e32 v219, v29, v3
	v_cvt_pk_bf16_f32 v206, v218, v219
	v_mul_f32_e32 v218, v30, v3
	v_mul_f32_e32 v219, v31, v3
	v_cvt_pk_bf16_f32 v207, v218, v219
	v_mul_f32_e32 v218, v44, v3
	v_mul_f32_e32 v219, v45, v3
	v_cvt_pk_bf16_f32 v214, v218, v219
	v_mul_f32_e32 v218, v46, v3
	v_mul_f32_e32 v219, v47, v3
	v_cvt_pk_bf16_f32 v215, v218, v219
	v_lshrrev_b32_e32 v216, 5, v158
	v_and_b32_e32 v217, 31, v158
	v_lshrrev_b32_e32 v218, 6, v150
	v_lshrrev_b32_e32 v219, 2, v218
	v_mul_u32_u24_e32 v218, 0x1200, v218
	v_mul_u32_u24_e32 v219, 0x4450, v219
	v_add3_u32 v218, v218, v219, 0
	v_mov_b32_e32 v221, 0x19800
	v_mul_u32_u24_e32 v219, 0x90, v217
	v_lshl_add_u32 v220, v216, 4, v219
	v_add3_u32 v220, v220, v218, v221
	v_lshrrev_b32_e32 v223, 3, v158
	v_and_b32_e32 v224, 7, v158
	v_mul_u32_u24_e32 v222, 0x90, v223
	v_lshl_add_u32 v222, v224, 4, v222
	v_add3_u32 v222, v222, v218, v221
	v_lshlrev_b32_e32 v228, 4, v224
	v_lshlrev_b32_e32 v229, 3, v216
	v_sub_u32_e32 v228, v228, v229
	v_ashrrev_i32_e32 v229, 31, v228
	v_lshl_add_u64 v[226:227], v[96:97], 0, v[228:229]
	v_readlane_b32 s100, v94, 0
	v_readlane_b32 s101, v95, 0
	v_permlane32_swap_b32_e32 v200, v202
	v_permlane32_swap_b32_e32 v201, v203
	v_permlane32_swap_b32_e32 v204, v206
	v_permlane32_swap_b32_e32 v205, v207
	v_permlane32_swap_b32_e32 v208, v210
	v_permlane32_swap_b32_e32 v209, v211
	v_permlane32_swap_b32_e32 v212, v214
	v_permlane32_swap_b32_e32 v213, v215
	s_nop 0
	ds_write_b128 v220, v[200:203]
	ds_write_b128 v220, v[204:207] offset:32
	ds_write_b128 v220, v[208:211] offset:64
	ds_write_b128 v220, v[212:215] offset:96
	v_add_u32_e32 v238, 0, v223
	v_mov_b32_e32 v240, s100
	v_mov_b32_e32 v241, s101
	v_mad_u64_u32 v[240:241], vcc, v238, s93, v[240:241]
	v_lshlrev_b64 v[240:241], 11, v[240:241]
	v_lshl_add_u64 v[240:241], v[240:241], 0, v[226:227]
	v_add_u32_e32 v238, 8, v223
	v_mov_b32_e32 v242, s100
	v_mov_b32_e32 v243, s101
	v_mad_u64_u32 v[242:243], vcc, v238, s93, v[242:243]
	v_lshlrev_b64 v[242:243], 11, v[242:243]
	v_lshl_add_u64 v[242:243], v[242:243], 0, v[226:227]
	v_add_u32_e32 v238, 16, v223
	v_mov_b32_e32 v244, s100
	v_mov_b32_e32 v245, s101
	v_mad_u64_u32 v[244:245], vcc, v238, s93, v[244:245]
	v_lshlrev_b64 v[244:245], 11, v[244:245]
	v_lshl_add_u64 v[244:245], v[244:245], 0, v[226:227]
	v_add_u32_e32 v238, 24, v223
	v_mov_b32_e32 v246, s100
	v_mov_b32_e32 v247, s101
	v_mad_u64_u32 v[246:247], vcc, v238, s93, v[246:247]
	v_lshlrev_b64 v[246:247], 11, v[246:247]
	v_lshl_add_u64 v[246:247], v[246:247], 0, v[226:227]
	s_waitcnt lgkmcnt(0)
	ds_read_b128 v[200:203], v222
	ds_read_b128 v[204:207], v222 offset:1152
	ds_read_b128 v[208:211], v222 offset:2304
	ds_read_b128 v[212:215], v222 offset:3456
	s_waitcnt lgkmcnt(3)
	global_store_dwordx4 v[240:241], v[200:203], off
	s_waitcnt lgkmcnt(2)
	global_store_dwordx4 v[242:243], v[204:207], off
	s_waitcnt lgkmcnt(1)
	global_store_dwordx4 v[244:245], v[208:211], off
	s_waitcnt lgkmcnt(0)
	global_store_dwordx4 v[246:247], v[212:215], off
	s_branch .LattnJ_1
